# row phases P1/P7/P10 take the 2048-token slab of blockIdx&7; the five barriers between token-local phase pairs sync only that slab's 32 workgroups (no L2 write-back) when every slab sits on one XCC, e
# speedup vs baseline: 1.0153x; 1.0099x over previous
; __device__ __forceinline__ XcdBarrier xcd_barrier_post(unsigned* bar, volatile LAS unsigned* st) {
;     XcdBarrier b; b.bar = bar; b.x = xb_xcc_id(); b.st = st;
;     if (threadIdx.x == 0) (void)xb_add(&bar[XB_XCNT(b.x)], 1u);
;     return b;
; }
; __device__ __forceinline__ void xcd_barrier_complete(unsigned* bar, unsigned x, unsigned& nloc, unsigned& nx) {
;     const unsigned G = gridDim.x * gridDim.y * gridDim.z;
;     unsigned sum, cnt, mine, sp = 0u;
;     for (;;) {
;         sum = 0u; cnt = 0u; mine = 0u;
; #pragma unroll
;         for (unsigned j = 0; j < 16; ++j) { const unsigned c = xb_ld(&bar[XB_XCNT(j)]); sum += c; cnt += (c > 0u) ? 1u : 0u; mine = (j == x) ? c : mine; }
;         if (sum == G) break;
;         __builtin_amdgcn_s_sleep(1);
;         if ((++sp & 255u) == 0u) { if (xb_ld(&bar[XB_TMO])) break; if (sp > XB_SPIN_CAP) { atomicAdd(&bar[XB_TMO], 1u); break; } }
;     }
;     nloc = mine > 0u ? mine : 1u; nx = cnt > 0u ? cnt : 1u;
; }
; __device__ __forceinline__ void xcd_barrier(const XcdBarrier& b) {
;     asm volatile("s_waitcnt vmcnt(0)" ::: "memory");
;     __syncthreads();
;     if (threadIdx.x == 0) {
;         unsigned* bar = b.bar;
;         __builtin_amdgcn_s_waitcnt(0);
;         unsigned nloc = b.st[0], nx = b.st[1];
;         if (nloc == 0u) { xcd_barrier_complete(bar, b.x, nloc, nx); b.st[0] = nloc; b.st[1] = nx; }
;         const unsigned old = xb_add(&bar[XB_XSUB(b.x)], 1u);
;         const unsigned gen = old / nloc;
;         if (old + 1u == (gen + 1u) * nloc) {
;             __builtin_amdgcn_fence(__ATOMIC_RELEASE, "agent");
;             asm volatile("s_waitcnt vmcnt(0)" ::: "memory");
;             const unsigned og = xb_add(&bar[XB_TOP], 1u);
;             const unsigned tg = og / nx;
;             if (og + 1u == (tg + 1u) * nx) xb_add(&bar[XB_TOPGEN], 1u);
; __global__ void __launch_bounds__(NTHREADS, 2) hybrid_block_fwd(Params P) {
;     ...
;     XcdBarrier bar = xcd_barrier_post((unsigned*)(P.ws + WS_CTL), MISC + 8);
;     ...
;     const int G = gridDim.x, bx = blockIdx.x;
;     unsigned char* ws = P.ws;
;     bf16_t* Zb = (bf16_t*)P.out;
;     if (PH(0)) for (int rep = 0; rep < REP_P0; ++rep) p0_prologue(P, lds, G);
;     if (P.out == nullptr) grid.sync();
;     GSYNC();
;     if (PH(1)) p1_rows(P, lds, G);
;     ...
;     __syncthreads(); p1_rows(P, lds, G);
;     ...
;     for (int rep = 0; rep < REP_SYNC; ++rep) GSYNC();
.LBB0_120:
	s_lshl_b32 s6, s3, 8
	s_add_u32 s6, s20, s6
	s_addc_u32 s7, s21, 0
	s_mov_b32 s100, 1
	s_mov_b32 s101, 0
	s_and_b32 s98, s2, 7
	s_lshl_b32 s10, s98, 2
	s_add_u32 s8, s58, s10
	s_addc_u32 s9, s59, 0
	s_add_u32 s8, s8, 0x900100
	s_addc_u32 s9, s9, 0
	s_lshl_b32 s10, 1, s3
	v_mov_b32_e32 v3, s10
	v_mov_b32_e32 v4, 0
	global_atomic_or v4, v3, s[8:9]
	s_lshl_b32 s98, s98, 8
	s_add_i32 s98, s98, 0x902400
	v_mov_b32_e32 v3, 1
	v_mov_b32_e32 v4, 0x1000
	global_atomic_add v3, v4, v3, s[6:7] offset:1024 sc0
	s_add_u32 s8, s58, 0x903400
	s_addc_u32 s9, s59, 0
	v_mov_b32_e32 v4, 0
	s_waitcnt lgkmcnt(0)
	v_mul_u32_u24_e32 v5, s100, v2
	v_mul_u32_u24_e32 v6, s100, v0
	s_waitcnt vmcnt(0)
	v_add_u32_e32 v3, 1, v3
	v_cmp_ne_u32_e32 vcc, v3, v5
	s_cbranch_vccnz .Lgbar_poll_0
	buffer_wbl2 sc1
	s_waitcnt vmcnt(0)
	v_mov_b32_e32 v3, 1
	global_atomic_add v4, v3, s[8:9]

; #define GSYNC() xcd_barrier(bar)
; __global__ void __launch_bounds__(NTHREADS, 2) hybrid_block_fwd(Params P) {
;     ...
;     GSYNC();
.Lgbar_done_0:
	buffer_inv sc1
	s_waitcnt vmcnt(0)
	s_add_u32 s8, s58, 0x900100
	s_addc_u32 s9, s59, 0
	v_mov_b32_e32 v4, 0
	global_load_dwordx4 v[8:11], v4, s[8:9] sc1
	global_load_dwordx4 v[12:15], v4, s[8:9] offset:16 sc1
	s_waitcnt vmcnt(0)
	s_cmpk_eq_u32 s92, 0x100
	s_cselect_b32 s99, 1, 0
	v_readfirstlane_b32 s10, v8
	s_bcnt1_i32_b32 s10, s10
	s_cmp_eq_u32 s10, 1
	s_cselect_b32 s99, s99, 0
	v_readfirstlane_b32 s10, v9
	s_bcnt1_i32_b32 s10, s10
	s_cmp_eq_u32 s10, 1
	s_cselect_b32 s99, s99, 0
	v_readfirstlane_b32 s10, v10
	s_bcnt1_i32_b32 s10, s10
	s_cmp_eq_u32 s10, 1
	s_cselect_b32 s99, s99, 0
	v_readfirstlane_b32 s10, v11
	s_bcnt1_i32_b32 s10, s10
	s_cmp_eq_u32 s10, 1
	s_cselect_b32 s99, s99, 0
	v_readfirstlane_b32 s10, v12
	s_bcnt1_i32_b32 s10, s10
	s_cmp_eq_u32 s10, 1
	s_cselect_b32 s99, s99, 0
	v_readfirstlane_b32 s10, v13
	s_bcnt1_i32_b32 s10, s10
	s_cmp_eq_u32 s10, 1
	s_cselect_b32 s99, s99, 0
	v_readfirstlane_b32 s10, v14
	s_bcnt1_i32_b32 s10, s10
	s_cmp_eq_u32 s10, 1
	s_cselect_b32 s99, s99, 0
	v_readfirstlane_b32 s10, v15
	s_bcnt1_i32_b32 s10, s10
	s_cmp_eq_u32 s10, 1
	s_cselect_b32 s99, s99, 0

; #define LAS __attribute__((address_space(3)))
; __device__ __forceinline__ unsigned pk2(float lo, float hi) { return pg8::cvtpk(lo, hi); }
; __device__ __forceinline__ void p1_rows(const Params& P, LAS unsigned char* lds, int G) {
;     ...
;     bf16_t* XN = (bf16_t*)(P.ws + WS_XN);
;     for (int m = blockIdx.x * 8 + wave; m < M; m += G * 8) {
;         const int b = m >> 13; const f32x4* xr = (const f32x4*)(P.x + (size_t)m * DM) + lane;
;         f32x4 v[8]; float ss = 0.f;
; #pragma unroll
;         for (int j = 0; j < 8; ++j) { v[j] = __builtin_nontemporal_load(xr + 64 * j); ss += (v[j][0] * v[j][0] + v[j][1] * v[j][1]) + (v[j][2] * v[j][2] + v[j][3] * v[j][3]); }
;         const float rstd = rsqrtf(wave_sum(ss) * (1.0f / DM) + RMS_EPS);
;         u32x2* o = (u32x2*)(XN + (size_t)m * DM) + lane;
; #pragma unroll
;         for (int j = 0; j < 8; ++j) { const f32x4 a = *(const LAS f32x4*)(TA + b * DM + 256 * j + 4 * lane), c = *(const LAS f32x4*)(TC + b * DM + 256 * j + 4 * lane);
;             const f32x4 h = v[j] * rstd * a + c; u32x2 w; w.x = pk2(h[0], h[1]); w.y = pk2(h[2], h[3]); o[64 * j] = w; }
;     }
.LBB0_166:
	s_or_b64 exec, exec, s[4:5]
	v_ashrrev_i32_e32 v0, 6, v8
	s_lshl_b32 s4, s2, 3
	v_writelane_b32 v241, s4, 15
	s_and_b32 s6, s2, 7
	s_lshl_b32 s6, s6, 11
	s_lshr_b32 s4, s2, 3
	s_lshl_b32 s4, s4, 3
	s_add_i32 s4, s4, s6
	s_lshl_b32 s6, s2, 3
	s_cmpk_eq_u32 s92, 0x100
	s_cselect_b32 s4, s4, s6
	v_add_u32_e32 v32, s4, v0
	s_movk_i32 s4, 0x4000
	v_cmp_gt_i32_e32 vcc, s4, v32
	v_mbcnt_lo_u32_b32 v208, -1, 0
	s_waitcnt lgkmcnt(0)
	s_barrier
	s_and_saveexec_b64 s[4:5], vcc
	s_cbranch_execz .LBB0_169
	v_mbcnt_hi_u32_b32 v0, -1, v208
	v_and_b32_e32 v1, 64, v0
	v_add_u32_e32 v1, 64, v1
	v_xor_b32_e32 v3, 1, v0
	v_cmp_lt_i32_e32 vcc, v3, v1
	v_and_b32_e32 v2, 63, v8
	v_ashrrev_i32_e32 v33, 31, v32
	v_cndmask_b32_e32 v3, v0, v3, vcc
	v_lshlrev_b32_e32 v38, 2, v3
	v_xor_b32_e32 v3, 2, v0
	v_cmp_lt_i32_e32 vcc, v3, v1
	s_mov_b64 s[6:7], 0x1000
	s_cmpk_eq_u32 s92, 0x100
	s_cselect_b32 s42, 0x100, s42
	s_ashr_i32 s43, s42, 31
	v_cndmask_b32_e32 v3, v0, v3, vcc
	v_lshlrev_b32_e32 v39, 2, v3
	v_xor_b32_e32 v3, 4, v0
	v_cmp_lt_i32_e32 vcc, v3, v1
	s_mov_b64 s[8:9], 0x6800000
	s_mov_b64 s[10:11], 0
	v_cndmask_b32_e32 v3, v0, v3, vcc
	v_lshlrev_b32_e32 v40, 2, v3
	v_xor_b32_e32 v3, 8, v0
	v_cmp_lt_i32_e32 vcc, v3, v1
	s_mov_b32 s12, 0x800000
	s_and_b32 s13, s2, 7
	s_lshl_b32 s13, s13, 11
	s_addk_i32 s13, 0x7ff
	s_cmpk_eq_u32 s92, 0x100
	s_cselect_b32 s13, s13, 0x3fff
	v_cndmask_b32_e32 v3, v0, v3, vcc
	v_lshlrev_b32_e32 v41, 2, v3
	v_xor_b32_e32 v3, 16, v0
	v_cmp_lt_i32_e32 vcc, v3, v1
	s_nop 1
	v_cndmask_b32_e32 v3, v0, v3, vcc
	v_lshlrev_b32_e32 v42, 2, v3
	v_xor_b32_e32 v3, 32, v0
	v_cmp_lt_i32_e32 vcc, v3, v1
	s_nop 1
	v_cndmask_b32_e32 v0, v0, v3, vcc
	v_lshlrev_b32_e32 v43, 2, v0
	v_lshlrev_b32_e32 v3, 4, v2
	v_lshlrev_b64 v[0:1], 13, v[32:33]
	v_or_b32_e32 v0, v0, v3
	v_lshl_add_u64 v[0:1], s[60:61], 0, v[0:1]
	v_lshl_add_u64 v[34:35], v[0:1], 0, s[6:7]
	v_lshlrev_b64 v[0:1], 12, v[32:33]
	v_lshl_or_b32 v0, v2, 3, v0
	v_lshl_add_u64 v[0:1], s[58:59], 0, v[0:1]
	v_add_u32_e32 v44, 0, v3
	s_lshl_b64 s[6:7], s[42:43], 13
	v_lshl_add_u64 v[36:37], v[0:1], 0, s[8:9]
	s_lshl_b64 s[8:9], s[42:43], 12
	v_mov_b32_e32 v33, 0x358637bd

; __device__ __forceinline__ unsigned xb_add(unsigned* p, unsigned v) { return __hip_atomic_fetch_add(p, v, __ATOMIC_RELAXED, __HIP_MEMORY_SCOPE_AGENT); }
; #define GSYNC() xcd_barrier(bar)
; __device__ __forceinline__ void xcd_barrier(const XcdBarrier& b) {
;     asm volatile("s_waitcnt vmcnt(0)" ::: "memory");
;     __syncthreads();
;     if (threadIdx.x == 0) {
;         unsigned* bar = b.bar;
;         __builtin_amdgcn_s_waitcnt(0);
;         unsigned nloc = b.st[0], nx = b.st[1];
;         if (nloc == 0u) { xcd_barrier_complete(bar, b.x, nloc, nx); b.st[0] = nloc; b.st[1] = nx; }
;         const unsigned old = xb_add(&bar[XB_XSUB(b.x)], 1u);
; __global__ void __launch_bounds__(NTHREADS, 2) hybrid_block_fwd(Params P) {
;     ...
;     for (int rep = 0; rep < REP_SYNC; ++rep) GSYNC();
.LBB0_169:
	s_lshl_b32 s42, s92, 3
	v_writelane_b32 v241, s14, 16
	s_nop 1
	v_writelane_b32 v241, s15, 17
	s_or_b64 exec, exec, s[4:5]
	s_mul_i32 s4, s93, s92
	s_mul_i32 s4, s4, s96
	s_add_u32 s96, s58, 0x900200
	s_addc_u32 s97, s59, 0
	v_writelane_b32 v241, s4, 12
	s_add_u32 s4, s58, 0x900400
	s_addc_u32 s5, s59, 0
	v_writelane_b32 v241, s4, 10
	s_waitcnt vmcnt(0)
	s_barrier
	s_nop 0
	v_writelane_b32 v241, s5, 11
	s_add_u32 s4, s58, 0x900500
	s_addc_u32 s5, s59, 0
	v_writelane_b32 v241, s4, 8
	s_nop 1
	v_writelane_b32 v241, s5, 9
	s_add_u32 s4, s58, 0x900600
	s_addc_u32 s5, s59, 0
	v_writelane_b32 v241, s4, 18
	s_nop 1
	v_writelane_b32 v241, s5, 19
	s_add_u32 s4, s58, 0x900700
	s_addc_u32 s5, s59, 0
	v_writelane_b32 v241, s4, 20
	s_nop 1
	v_writelane_b32 v241, s5, 21
	s_add_u32 s4, s58, 0x900800
	s_addc_u32 s5, s59, 0
	v_writelane_b32 v241, s4, 22
	s_nop 1
	v_writelane_b32 v241, s5, 23
	s_add_u32 s4, s58, 0x900900
	s_addc_u32 s5, s59, 0
	v_writelane_b32 v241, s4, 24
	s_nop 1
	v_writelane_b32 v241, s5, 25
	s_add_u32 s4, s58, 0x900a00
	s_addc_u32 s5, s59, 0
	v_writelane_b32 v241, s4, 26
	s_nop 1
	v_writelane_b32 v241, s5, 27
	s_add_u32 s4, s58, 0x900b00
	s_addc_u32 s5, s59, 0
	v_writelane_b32 v241, s4, 28
	s_nop 1
	v_writelane_b32 v241, s5, 29
	s_add_u32 s4, s58, 0x900c00
	s_addc_u32 s5, s59, 0
	s_add_u32 s6, s58, 0x900d00
	s_addc_u32 s7, s59, 0
	s_add_u32 s8, s58, 0x900e00
	s_addc_u32 s9, s59, 0
	s_add_u32 s10, s58, 0x900f00
	s_addc_u32 s11, s59, 0
	s_add_u32 s12, s58, 0x901000
	s_addc_u32 s13, s59, 0
	s_add_u32 s14, s58, 0x901100
	s_addc_u32 s15, s59, 0
	s_add_u32 s16, s58, 0x901200
	s_addc_u32 s17, s59, 0
	s_add_u32 s18, s58, 0x901300
	s_addc_u32 s19, s59, 0
	v_writelane_b32 v241, s4, 30
	s_cmp_eq_u32 s3, 15
	s_nop 0
	v_writelane_b32 v241, s5, 31
	s_cselect_b64 s[4:5], -1, 0
	v_writelane_b32 v241, s4, 32
	s_cmp_eq_u32 s3, 14
	s_nop 0
	v_writelane_b32 v241, s5, 33
	s_cselect_b64 s[4:5], -1, 0
	v_writelane_b32 v241, s4, 34
	s_cmp_eq_u32 s3, 13
	s_nop 0
	v_writelane_b32 v241, s5, 35
	s_cselect_b64 s[4:5], -1, 0
	v_writelane_b32 v241, s4, 36
	s_cmp_eq_u32 s3, 12
	s_nop 0
	v_writelane_b32 v241, s5, 37
	s_cselect_b64 s[4:5], -1, 0
	v_writelane_b32 v241, s4, 38
	s_cmp_eq_u32 s3, 11
	s_nop 0
	v_writelane_b32 v241, s5, 39
	s_cselect_b64 s[4:5], -1, 0
	v_writelane_b32 v241, s4, 40
	s_cmp_eq_u32 s3, 10
	s_nop 0
	v_writelane_b32 v241, s5, 41
	s_cselect_b64 s[4:5], -1, 0
	v_writelane_b32 v241, s4, 42
	s_cmp_eq_u32 s3, 9
	s_nop 0
	v_writelane_b32 v241, s5, 43
	s_cselect_b64 s[4:5], -1, 0
	v_writelane_b32 v241, s4, 44
	s_cmp_eq_u32 s3, 8
	s_nop 0
	v_writelane_b32 v241, s5, 45
	s_cselect_b64 s[4:5], -1, 0
	v_writelane_b32 v241, s4, 46
	s_cmp_eq_u32 s3, 7
	s_nop 0
	v_writelane_b32 v241, s5, 47
	s_cselect_b64 s[4:5], -1, 0
	v_writelane_b32 v241, s4, 48
	s_cmp_eq_u32 s3, 6
	s_nop 0
	v_writelane_b32 v241, s5, 49
	s_cselect_b64 s[4:5], -1, 0
	v_writelane_b32 v241, s4, 50
	s_cmp_eq_u32 s3, 5
	s_nop 0
	v_writelane_b32 v241, s5, 51
	s_cselect_b64 s[4:5], -1, 0
	v_writelane_b32 v241, s4, 52
	s_cmp_eq_u32 s3, 4
	s_nop 0
	v_writelane_b32 v241, s5, 53
	s_cselect_b64 s[4:5], -1, 0
	v_writelane_b32 v241, s4, 54
	s_cmp_eq_u32 s3, 3
	s_nop 0
	v_writelane_b32 v241, s5, 55
	s_cselect_b64 s[4:5], -1, 0
	v_writelane_b32 v241, s4, 56
	s_cmp_eq_u32 s3, 2
	s_nop 0
	v_writelane_b32 v241, s5, 57
	s_cselect_b64 s[4:5], -1, 0
	v_writelane_b32 v241, s4, 58
	s_cmp_eq_u32 s3, 1
	s_nop 0
	v_writelane_b32 v241, s5, 59
	s_cselect_b64 s[4:5], -1, 0
	v_writelane_b32 v241, s4, 60
	s_cmp_eq_u32 s3, 0
	s_nop 0
	v_writelane_b32 v241, s5, 61
	s_cselect_b64 s[4:5], -1, 0
	s_lshl_b32 s3, s3, 8
	s_add_u32 s3, s20, s3
	v_writelane_b32 v241, s4, 62
	s_addc_u32 s20, s21, 0
	s_nop 0
	v_writelane_b32 v241, s5, 63
	s_add_u32 s4, s3, 0x1400
	s_addc_u32 s5, s20, 0
	v_writelane_b32 v240, s4, 0
	s_nop 1
	v_writelane_b32 v240, s5, 1
	s_add_u32 s4, s3, 0x2400
	s_addc_u32 s5, s20, 0
	v_writelane_b32 v240, s4, 2
	s_nop 1
	v_writelane_b32 v240, s5, 3
	s_add_u32 s4, s58, 0x903400
	s_addc_u32 s5, s59, 0
	v_writelane_b32 v240, s4, 4
	s_nop 1
	v_writelane_b32 v240, s5, 5
	s_add_u32 s4, s58, 0x903500
	s_addc_u32 s5, s59, 0
	v_writelane_b32 v240, s4, 6
	s_nop 1
	v_writelane_b32 v240, s5, 7
	s_mov_b64 s[20:21], exec
	v_readlane_b32 s22, v241, 0
	v_readlane_b32 s23, v241, 1
	s_and_b64 s[22:23], s[20:21], s[22:23]
	s_mov_b64 exec, s[22:23]
	s_cbranch_execz .LBB0_221
	s_add_i32 s3, 0, 0x20160
	v_mov_b32_e32 v0, s3
	s_waitcnt vmcnt(0) expcnt(0) lgkmcnt(0)
	ds_read_b32 v2, v0
	s_add_i32 s3, 0, 0x20164
	v_mov_b32_e32 v0, s3
	ds_read_b32 v0, v0
	s_waitcnt lgkmcnt(1)
	v_cmp_ne_u32_e32 vcc, 0, v2
	s_cbranch_vccnz .LBB0_185
	s_mov_b32 s3, 1
	v_mov_b32_e32 v16, 0
	s_branch .LBB0_173

; __device__ __forceinline__ unsigned xb_ld(unsigned* p)              { return __hip_atomic_load(p, __ATOMIC_RELAXED, __HIP_MEMORY_SCOPE_AGENT); }
; __device__ __forceinline__ unsigned xb_add(unsigned* p, unsigned v) { return __hip_atomic_fetch_add(p, v, __ATOMIC_RELAXED, __HIP_MEMORY_SCOPE_AGENT); }
; #define XB_SPIN(cond, bar) do { unsigned _sp = 0; while (cond) { __builtin_amdgcn_s_sleep(1); \
;     if ((++_sp & 255u) == 0u) { if (xb_ld(&(bar)[XB_TMO])) break; if (_sp > XB_SPIN_CAP) { atomicAdd(&(bar)[XB_TMO], 1u); break; } } } } while (0)
; __device__ __forceinline__ void xcd_barrier(const XcdBarrier& b) {
;     asm volatile("s_waitcnt vmcnt(0)" ::: "memory");
;     __syncthreads();
;     if (threadIdx.x == 0) {
;         unsigned* bar = b.bar;
;         __builtin_amdgcn_s_waitcnt(0);
;         unsigned nloc = b.st[0], nx = b.st[1];
;         if (nloc == 0u) { xcd_barrier_complete(bar, b.x, nloc, nx); b.st[0] = nloc; b.st[1] = nx; }
;         const unsigned old = xb_add(&bar[XB_XSUB(b.x)], 1u);
;         const unsigned gen = old / nloc;
;         if (old + 1u == (gen + 1u) * nloc) {
;             __builtin_amdgcn_fence(__ATOMIC_RELEASE, "agent");
;             asm volatile("s_waitcnt vmcnt(0)" ::: "memory");
;             const unsigned og = xb_add(&bar[XB_TOP], 1u);
;             const unsigned tg = og / nx;
;             if (og + 1u == (tg + 1u) * nx) xb_add(&bar[XB_TOPGEN], 1u);
;             else XB_SPIN(xb_ld(&bar[XB_TOPGEN]) == tg, bar);
;             __builtin_amdgcn_fence(__ATOMIC_ACQUIRE, "agent");
;             xb_add(&bar[XB_XGEN(b.x)], 1u);
;             asm volatile("s_waitcnt vmcnt(0)" ::: "memory");
;         } else {
;             XB_SPIN(xb_ld(&bar[XB_XGEN(b.x)]) == gen, bar);
;             __builtin_amdgcn_fence(__ATOMIC_ACQUIRE, "agent");
;             asm volatile("s_waitcnt vmcnt(0)" ::: "memory");
;         }
;     }
;     __syncthreads();
; }
.LBB0_185:
	s_cmp_eq_u32 s99, 0
	s_cbranch_scc1 .Lgbar_glob_1
	s_add_i32 s101, s101, 1
	s_add_u32 s4, s58, s98
	s_addc_u32 s5, s59, 0
	v_mov_b32_e32 v3, 1
	v_mov_b32_e32 v4, 0
	global_atomic_add v4, v3, s[4:5]
	v_mov_b32_e32 v6, s101
	v_lshlrev_b32_e32 v6, 5, v6
	v_mov_b32_e32 v5, 0

; __device__ __forceinline__ unsigned xb_ld(unsigned* p)              { return __hip_atomic_load(p, __ATOMIC_RELAXED, __HIP_MEMORY_SCOPE_AGENT); }
; __device__ __forceinline__ unsigned xb_add(unsigned* p, unsigned v) { return __hip_atomic_fetch_add(p, v, __ATOMIC_RELAXED, __HIP_MEMORY_SCOPE_AGENT); }
; #define XB_SPIN(cond, bar) do { unsigned _sp = 0; while (cond) { __builtin_amdgcn_s_sleep(1); \
;     if ((++_sp & 255u) == 0u) { if (xb_ld(&(bar)[XB_TMO])) break; if (_sp > XB_SPIN_CAP) { atomicAdd(&(bar)[XB_TMO], 1u); break; } } } } while (0)
; __device__ __forceinline__ void xcd_barrier(const XcdBarrier& b) {
;     ...
;         const unsigned old = xb_add(&bar[XB_XSUB(b.x)], 1u);
;         const unsigned gen = old / nloc;
;         if (old + 1u == (gen + 1u) * nloc) {
;             __builtin_amdgcn_fence(__ATOMIC_RELEASE, "agent");
;             asm volatile("s_waitcnt vmcnt(0)" ::: "memory");
;             const unsigned og = xb_add(&bar[XB_TOP], 1u);
;             const unsigned tg = og / nx;
;             if (og + 1u == (tg + 1u) * nx) xb_add(&bar[XB_TOPGEN], 1u);
;             else XB_SPIN(xb_ld(&bar[XB_TOPGEN]) == tg, bar);
;             __builtin_amdgcn_fence(__ATOMIC_ACQUIRE, "agent");
;             xb_add(&bar[XB_XGEN(b.x)], 1u);
;             asm volatile("s_waitcnt vmcnt(0)" ::: "memory");
;         } else {
;             XB_SPIN(xb_ld(&bar[XB_XGEN(b.x)]) == gen, bar);
;             __builtin_amdgcn_fence(__ATOMIC_ACQUIRE, "agent");
;             asm volatile("s_waitcnt vmcnt(0)" ::: "memory");
;         }
;     }
;     __syncthreads();
; }
.Lgbar_ldone_1:
	buffer_inv sc1
	s_waitcnt vmcnt(0) lgkmcnt(0)
	s_branch .Lgbar_end_1
.Lgbar_glob_1:
	s_add_i32 s100, s100, 1
	v_readlane_b32 s4, v240, 0
	v_readlane_b32 s5, v240, 1
	v_mov_b32_e32 v3, 1
	v_mov_b32_e32 v4, 0
	s_nop 4
	global_atomic_add v3, v4, v3, s[4:5] sc0
	v_readlane_b32 s4, v240, 4
	v_readlane_b32 s5, v240, 5
	s_waitcnt lgkmcnt(0)
	v_mul_u32_u24_e32 v5, s100, v2
	v_mul_u32_u24_e32 v6, s100, v0
	s_waitcnt vmcnt(0)
	v_add_u32_e32 v3, 1, v3
	v_cmp_ne_u32_e32 vcc, v3, v5
	s_cbranch_vccnz .Lgbar_poll_1
	buffer_wbl2 sc1
	s_waitcnt vmcnt(0)
	v_mov_b32_e32 v3, 1
	global_atomic_add v4, v3, s[4:5]

;     __host__ __device__ bool next(int i, Unit& u) const {
;         const long L = (long)i * G + c; if (L >= nwg) return false;
;         int wgid = (int)L; { const int q = nwg / NXCD, r = nwg % NXCD, xcd = wgid % NXCD, off = wgid / NXCD; wgid = (xcd < r ? xcd * (q + 1) : r * (q + 1) + (xcd - r) * q) + off; }
;         const int nig = WGM * nN, gid = wgid / nig, fm = gid * WGM, gsz = (nM - fm) < WGM ? (nM - fm) : WGM;
;         u.pm = fm + ((wgid % nig) % gsz); u.pn = (wgid % nig) / gsz; return true;
; __global__ void __launch_bounds__(NTHREADS, 2) hybrid_block_fwd(Params P) {
;     ...
;     if (PH(2)) { pg8::Gemm g{(const bf16_t*)(ws + WS_XN), (const bf16_t*)(ws + WS_WIN), M, ZC, DM, DM, DM}; pg8::StaticOrder S; S.init(M, ZC, G, bx);
;       pg8::EpiPlain E{Zb, ZC}; pg8::gemm_phase<pg8::EpiPlain, pg8::StaticOrder, P2_ALIGN, P2_SP2>(lds, g, S, E); }
.Lgbar_end_1:
.LBB0_221:
	s_or_b64 exec, exec, s[20:21]
	s_add_u32 s20, s58, 0x6800000
	s_addc_u32 s21, s59, 0
	s_cmpk_lt_i32 s2, 0x400
	v_mov_b32_e32 v8, v168
	s_cselect_b64 s[4:5], -1, 0
	s_waitcnt lgkmcnt(0)
	s_barrier
	v_writelane_b32 v240, s4, 10
	v_readfirstlane_b32 s27, v8
	s_and_b64 vcc, exec, s[4:5]
	v_writelane_b32 v240, s5, 11
	s_cbranch_vccz .LBB0_245
	s_ashr_i32 s3, s2, 31
	s_lshr_b32 s22, s3, 29
	s_add_i32 s24, s2, s22
	s_and_b32 s22, s24, -8
	s_sub_i32 s26, s2, s22
	s_cmp_gt_i32 s26, -1
	s_cbranch_scc0 .LBB0_224
	s_lshl_b32 s25, s26, 7
	s_cbranch_execz .LBB0_225
	s_branch .LBB0_226

; #define LAS __attribute__((address_space(3)))
; __device__ __forceinline__ void p7_rows(const Params& P, LAS unsigned char* lds, int G) {
;     ...
;     const float* ada = (const float*)(P.ws + WS_ADA);
;     LAS float* TA = (LAS float*)lds; LAS float* TB = TA + 2 * DM; LAS float* TC = TB + 2 * DM;
;     for (int idx = tid; idx < 2 * DM; idx += NTHREADS) { const int b = idx >> 11, col = idx & (DM - 1); const float* ab = ada + (size_t)b * NADA;
;         TA[idx] = ab[2 * DM + col] * P.g_post_mix[col]; TB[idx] = P.g_pre_ffn[col] * (1.0f + ab[4 * DM + col]); TC[idx] = ab[3 * DM + col]; }
;     __syncthreads();
;     const bf16_t* O = (const bf16_t*)(P.ws + WS_O); bf16_t* XN = (bf16_t*)(P.ws + WS_XN);
;     for (int m = blockIdx.x * 8 + wave; m < M; m += G * 8) {
;         const int b = m >> 13; const f32x4* xr = (const f32x4*)(P.x + (size_t)m * DM) + lane; const u32x2* orow = (const u32x2*)(O + (size_t)m * DM) + lane;
.Lgbar_end_7:
.LBB0_791:
	s_or_b64 exec, exec, s[0:1]
	s_waitcnt lgkmcnt(0)
	v_mov_b32_e32 v0, v168
	s_movk_i32 s0, 0x1000
	s_barrier
	s_nop 0
	v_cmp_gt_i32_e32 vcc, s0, v0
	s_and_saveexec_b64 s[22:23], vcc
	s_cbranch_execz .LBB0_801
	v_lshlrev_b32_e32 v1, 2, v0
	v_readlane_b32 s4, v241, 16
	v_readlane_b32 s5, v241, 17
	s_nop 1
	s_add_u32 s8, s72, 0x0
	s_addc_u32 s9, s73, 0
	global_load_dword v20, v1, s[8:9]
	s_add_u32 s8, s72, 0x800
	s_addc_u32 s9, s73, 0
	global_load_dword v21, v1, s[8:9]
	s_add_u32 s8, s72, 0x1000
	s_addc_u32 s9, s73, 0
	global_load_dword v22, v1, s[8:9]
	s_add_u32 s8, s72, 0x1800
	s_addc_u32 s9, s73, 0
	global_load_dword v23, v1, s[8:9]
	s_add_u32 s8, s46, 0x0
	s_addc_u32 s9, s47, 0
	global_load_dword v24, v1, s[8:9]
	s_add_u32 s8, s46, 0x800
	s_addc_u32 s9, s47, 0
	global_load_dword v25, v1, s[8:9]
	s_add_u32 s8, s46, 0x1000
	s_addc_u32 s9, s47, 0
	global_load_dword v26, v1, s[8:9]
	s_add_u32 s8, s46, 0x1800
	s_addc_u32 s9, s47, 0
	global_load_dword v27, v1, s[8:9]
	s_add_u32 s8, s4, 0x4000
	s_addc_u32 s9, s5, 0
	global_load_dword v28, v1, s[8:9]
	s_add_u32 s8, s4, 0x8000
	s_addc_u32 s9, s5, 0
	global_load_dword v36, v1, s[8:9]
	s_add_u32 s8, s4, 0x6000
	s_addc_u32 s9, s5, 0
	global_load_dword v44, v1, s[8:9]
	s_add_u32 s8, s4, 0x4800
	s_addc_u32 s9, s5, 0
	global_load_dword v29, v1, s[8:9]
	s_add_u32 s8, s4, 0x8800
	s_addc_u32 s9, s5, 0
	global_load_dword v37, v1, s[8:9]
	s_add_u32 s8, s4, 0x6800
	s_addc_u32 s9, s5, 0
	global_load_dword v45, v1, s[8:9]
	s_add_u32 s8, s4, 0x5000
	s_addc_u32 s9, s5, 0
	global_load_dword v30, v1, s[8:9]
	s_add_u32 s8, s4, 0x9000
	s_addc_u32 s9, s5, 0
	global_load_dword v38, v1, s[8:9]
	s_add_u32 s8, s4, 0x7000
	s_addc_u32 s9, s5, 0
	global_load_dword v46, v1, s[8:9]
	s_add_u32 s8, s4, 0x5800
	s_addc_u32 s9, s5, 0
	global_load_dword v31, v1, s[8:9]
	s_add_u32 s8, s4, 0x9800
	s_addc_u32 s9, s5, 0
	global_load_dword v39, v1, s[8:9]
	s_add_u32 s8, s4, 0x7800
	s_addc_u32 s9, s5, 0
	global_load_dword v47, v1, s[8:9]
	s_add_u32 s8, s4, 0x10000
	s_addc_u32 s9, s5, 0
	global_load_dword v32, v1, s[8:9]
	s_add_u32 s8, s4, 0x14000
	s_addc_u32 s9, s5, 0
	global_load_dword v40, v1, s[8:9]
	s_add_u32 s8, s4, 0x12000
	s_addc_u32 s9, s5, 0
	global_load_dword v48, v1, s[8:9]
	s_add_u32 s8, s4, 0x10800
	s_addc_u32 s9, s5, 0
	global_load_dword v33, v1, s[8:9]
	s_add_u32 s8, s4, 0x14800
	s_addc_u32 s9, s5, 0
	global_load_dword v41, v1, s[8:9]
	s_add_u32 s8, s4, 0x12800
	s_addc_u32 s9, s5, 0
	global_load_dword v49, v1, s[8:9]
	s_add_u32 s8, s4, 0x11000
	s_addc_u32 s9, s5, 0
	global_load_dword v34, v1, s[8:9]
	s_add_u32 s8, s4, 0x15000
	s_addc_u32 s9, s5, 0
	global_load_dword v42, v1, s[8:9]
	s_add_u32 s8, s4, 0x13000
	s_addc_u32 s9, s5, 0
	global_load_dword v50, v1, s[8:9]
	s_add_u32 s8, s4, 0x11800
	s_addc_u32 s9, s5, 0
	global_load_dword v35, v1, s[8:9]
	s_add_u32 s8, s4, 0x15800
	s_addc_u32 s9, s5, 0
	global_load_dword v43, v1, s[8:9]
	s_add_u32 s8, s4, 0x13800
	s_addc_u32 s9, s5, 0
	global_load_dword v51, v1, s[8:9]
	s_waitcnt vmcnt(0)
	v_mul_f32_e32 v52, v28, v20
	v_add_f32_e32 v53, 1.0, v36
	ds_write_b32 v1, v52
	v_mul_f32_e32 v53, v24, v53
	ds_write_b32 v1, v53 offset:16384
	ds_write_b32 v1, v44 offset:32768
	v_mul_f32_e32 v54, v29, v21
	v_add_f32_e32 v55, 1.0, v37
	ds_write_b32 v1, v54 offset:2048
	v_mul_f32_e32 v55, v25, v55
	ds_write_b32 v1, v55 offset:18432
	ds_write_b32 v1, v45 offset:34816
	v_mul_f32_e32 v56, v30, v22
	v_add_f32_e32 v57, 1.0, v38
	ds_write_b32 v1, v56 offset:4096
	v_mul_f32_e32 v57, v26, v57
	ds_write_b32 v1, v57 offset:20480
	ds_write_b32 v1, v46 offset:36864
	v_mul_f32_e32 v58, v31, v23
	v_add_f32_e32 v59, 1.0, v39
	ds_write_b32 v1, v58 offset:6144
	v_mul_f32_e32 v59, v27, v59
	ds_write_b32 v1, v59 offset:22528
	ds_write_b32 v1, v47 offset:38912
	v_mul_f32_e32 v60, v32, v20
	v_add_f32_e32 v61, 1.0, v40
	ds_write_b32 v1, v60 offset:8192
	v_mul_f32_e32 v61, v24, v61
	ds_write_b32 v1, v61 offset:24576
	ds_write_b32 v1, v48 offset:40960
	v_mul_f32_e32 v62, v33, v21
	v_add_f32_e32 v63, 1.0, v41
	ds_write_b32 v1, v62 offset:10240
	v_mul_f32_e32 v63, v25, v63
	ds_write_b32 v1, v63 offset:26624
	ds_write_b32 v1, v49 offset:43008
	v_mul_f32_e32 v64, v34, v22
	v_add_f32_e32 v65, 1.0, v42
	ds_write_b32 v1, v64 offset:12288
	v_mul_f32_e32 v65, v26, v65
	ds_write_b32 v1, v65 offset:28672
	ds_write_b32 v1, v50 offset:45056
	v_mul_f32_e32 v66, v35, v23
	v_add_f32_e32 v67, 1.0, v43
	ds_write_b32 v1, v66 offset:14336
	v_mul_f32_e32 v67, v27, v67
	ds_write_b32 v1, v67 offset:30720
	ds_write_b32 v1, v51 offset:47104
.LBB0_801:
	s_or_b64 exec, exec, s[22:23]
	v_ashrrev_i32_e32 v1, 6, v0
	s_and_b32 s1, s2, 7
	s_lshl_b32 s1, s1, 11
	s_lshr_b32 s0, s2, 3
	s_lshl_b32 s0, s0, 3
	s_add_i32 s0, s0, s1
	s_lshl_b32 s1, s2, 3
	s_cmpk_eq_u32 s92, 0x100
	s_cselect_b32 s0, s0, s1
	s_waitcnt lgkmcnt(0)
	s_barrier
	v_add_u32_e32 v32, s0, v1
	s_movk_i32 s0, 0x4000
	v_cmp_gt_i32_e32 vcc, s0, v32
	s_and_saveexec_b64 s[0:1], vcc
	s_cbranch_execz .LBB0_804
	v_and_b32_e32 v2, 63, v0
	v_mbcnt_hi_u32_b32 v0, -1, v208
	v_and_b32_e32 v1, 64, v0
	v_add_u32_e32 v1, 64, v1
	v_xor_b32_e32 v3, 1, v0
	v_cmp_lt_i32_e32 vcc, v3, v1
	v_ashrrev_i32_e32 v33, 31, v32
	s_mov_b64 s[22:23], 0x1000
	v_cndmask_b32_e32 v3, v0, v3, vcc
	v_lshlrev_b32_e32 v74, 2, v3
	v_xor_b32_e32 v3, 2, v0
	v_cmp_lt_i32_e32 vcc, v3, v1
	s_cmpk_eq_u32 s92, 0x100
	s_cselect_b32 s42, 0x100, s42
	s_ashr_i32 s43, s42, 31
	s_mov_b64 s[26:27], 0x1a000000
	v_cndmask_b32_e32 v3, v0, v3, vcc
	v_lshlrev_b32_e32 v75, 2, v3
	v_xor_b32_e32 v3, 4, v0
	v_cmp_lt_i32_e32 vcc, v3, v1
	s_mov_b64 s[30:31], 0
	s_mov_b32 s3, 0x800000
	v_cndmask_b32_e32 v3, v0, v3, vcc
	v_lshlrev_b32_e32 v76, 2, v3
	v_xor_b32_e32 v3, 8, v0
	v_cmp_lt_i32_e32 vcc, v3, v1
	s_nop 1
	v_cndmask_b32_e32 v3, v0, v3, vcc
	v_lshlrev_b32_e32 v77, 2, v3
	v_xor_b32_e32 v3, 16, v0
	v_cmp_lt_i32_e32 vcc, v3, v1
	s_nop 1
	v_cndmask_b32_e32 v3, v0, v3, vcc
	v_lshlrev_b32_e32 v78, 2, v3
	v_xor_b32_e32 v3, 32, v0
	v_cmp_lt_i32_e32 vcc, v3, v1
	s_nop 1
	v_cndmask_b32_e32 v0, v0, v3, vcc
	v_lshlrev_b32_e32 v79, 2, v0
	v_lshlrev_b32_e32 v3, 4, v2
	v_lshlrev_b64 v[0:1], 13, v[32:33]
	v_or_b32_e32 v0, v0, v3
	v_lshl_add_u64 v[0:1], s[60:61], 0, v[0:1]
	v_lshl_add_u64 v[34:35], v[0:1], 0, s[22:23]
	v_lshlrev_b64 v[0:1], 12, v[32:33]
	v_lshl_or_b32 v0, v2, 3, v0
	v_lshl_add_u64 v[0:1], s[58:59], 0, v[0:1]
	v_add_u32_e32 v80, 0, v3
	s_lshl_b64 s[22:23], s[42:43], 13
	v_lshl_add_u64 v[36:37], v[0:1], 0, s[26:27]
	s_lshl_b64 s[26:27], s[42:43], 12
	v_mov_b32_e32 v33, 0x358637bd
; #define LAS __attribute__((address_space(3)))
; __device__ __forceinline__ unsigned pk2(float lo, float hi) { return pg8::cvtpk(lo, hi); }
; __device__ __forceinline__ void p7_rows(const Params& P, LAS unsigned char* lds, int G) {
;     ...
;     for (int m = blockIdx.x * 8 + wave; m < M; m += G * 8) {
;         const int b = m >> 13; const f32x4* xr = (const f32x4*)(P.x + (size_t)m * DM) + lane; const u32x2* orow = (const u32x2*)(O + (size_t)m * DM) + lane;
;         f32x4 v[8], xv[8]; float ss = 0.f;
; #pragma unroll
;         for (int j = 0; j < 8; ++j) xv[j] = __builtin_nontemporal_load(xr + 64 * j);
; #pragma unroll
;         for (int j = 0; j < 8; ++j) { const u32x2 w = __builtin_nontemporal_load(orow + 64 * j); v[j][0] = __uint_as_float(w.x << 16); v[j][1] = __uint_as_float(w.x & 0xffff0000u); v[j][2] = __uint_as_float(w.y << 16); v[j][3] = __uint_as_float(w.y & 0xffff0000u);
;             ss += (v[j][0] * v[j][0] + v[j][1] * v[j][1]) + (v[j][2] * v[j][2] + v[j][3] * v[j][3]); }
;         const float rstd = rsqrtf(wave_sum(ss) * (1.0f / DM) + RMS_EPS);
;         float s2 = 0.f; u32x2* x1r = (u32x2*)((bf16_t*)(P.ws + WS_X1) + (size_t)m * DM) + lane;
; #pragma unroll
;         for (int j = 0; j < 8; ++j) { const f32x4 a = *(const LAS f32x4*)(TA + b * DM + 256 * j + 4 * lane); const f32x4 x1 = xv[j] + v[j] * rstd * a; v[j] = x1; { u32x2 w; w.x = pk2(x1[0], x1[1]); w.y = pk2(x1[2], x1[3]); __builtin_nontemporal_store(w, x1r + 64 * j); }
.LBB0_803:
	v_add_co_u32_e32 v38, vcc, 0xf0800000, v36
	s_mov_b32 s33, 0xf0801000
	s_nop 0
	v_addc_co_u32_e32 v39, vcc, -1, v37, vcc
	v_add_co_u32_e32 v40, vcc, s33, v36
	global_load_dwordx4 v[28:31], v[34:35], off offset:-4096 nt
	global_load_dwordx4 v[24:27], v[34:35], off offset:-3072 nt
	global_load_dwordx4 v[20:23], v[34:35], off offset:-2048 nt
	global_load_dwordx4 v[16:19], v[34:35], off offset:-1024 nt
	global_load_dwordx4 v[12:15], v[34:35], off nt
	global_load_dwordx4 v[8:11], v[34:35], off offset:1024 nt
	global_load_dwordx4 v[4:7], v[34:35], off offset:2048 nt
	global_load_dwordx4 v[0:3], v[34:35], off offset:3072 nt
	v_addc_co_u32_e32 v41, vcc, -1, v37, vcc
	global_load_dwordx2 v[38:39], v[38:39], off nt
	s_mov_b32 s33, 0xec800000
	global_load_dwordx2 v[42:43], v[40:41], off offset:-3584 nt
	global_load_dwordx2 v[44:45], v[40:41], off offset:-3072 nt
	v_lshl_add_u64 v[34:35], v[34:35], 0, s[22:23]
	s_waitcnt vmcnt(2)
	v_and_b32_e32 v67, 0xffff0000, v38
	v_and_b32_e32 v69, 0xffff0000, v39
	v_lshlrev_b32_e32 v66, 16, v38
	s_waitcnt vmcnt(0)
	v_lshlrev_b32_e32 v58, 16, v44
	v_and_b32_e32 v59, 0xffff0000, v44
	v_lshlrev_b32_e32 v60, 16, v45
	v_and_b32_e32 v61, 0xffff0000, v45
	global_load_dwordx2 v[44:45], v[40:41], off offset:-2560 nt
	v_lshlrev_b32_e32 v68, 16, v39
	v_mul_f32_e32 v38, v69, v69
	v_and_b32_e32 v73, 0xffff0000, v43
	v_and_b32_e32 v72, 0xffff0000, v42
	v_pk_fma_f32 v[38:39], v[68:69], v[68:69], v[38:39] op_sel_hi:[1,1,0]
	v_lshlrev_b32_e32 v71, 16, v43
	v_lshlrev_b32_e32 v70, 16, v42
	v_pk_mul_f32 v[42:43], v[72:73], v[72:73]
	v_mov_b32_e32 v46, v38
	v_pk_fma_f32 v[42:43], v[70:71], v[70:71], v[42:43]
	s_waitcnt vmcnt(0)
	v_lshlrev_b32_e32 v55, 16, v44
	v_and_b32_e32 v51, 0xffff0000, v44
	v_mul_f32_e32 v44, v67, v67
	v_lshlrev_b32_e32 v48, 16, v45
	v_and_b32_e32 v49, 0xffff0000, v45
	v_pk_fma_f32 v[44:45], v[66:67], v[66:67], v[44:45] op_sel_hi:[1,1,0]
	v_mov_b32_e32 v47, v55
	v_mov_b32_e32 v54, v44
	v_mul_f32_e32 v50, v51, v51
	v_pk_add_f32 v[38:39], v[44:45], v[38:39]
	v_pk_mul_f32 v[44:45], v[54:55], v[46:47]
	v_pk_add_f32 v[42:43], v[42:43], v[42:43] op_sel:[0,1] op_sel_hi:[1,0]
	v_mov_b32_e32 v39, v45
	v_mov_b32_e32 v43, v50
	v_pk_add_f32 v[38:39], v[38:39], v[42:43]
	v_mul_f32_e32 v42, v59, v59
	v_mul_f32_e32 v44, v61, v61
	v_mul_f32_e32 v52, v48, v48
	v_mul_f32_e32 v53, v49, v49
	v_pk_fma_f32 v[42:43], v[58:59], v[58:59], v[42:43] op_sel_hi:[1,1,0]
	v_pk_fma_f32 v[44:45], v[60:61], v[60:61], v[44:45] op_sel_hi:[1,1,0]
	v_mov_b32_e32 v43, v52
	v_mov_b32_e32 v45, v53
	v_pk_add_f32 v[42:43], v[42:43], v[44:45]
	s_nop 0
	v_pk_add_f32 v[82:83], v[38:39], v[42:43]
	global_load_dwordx2 v[38:39], v[40:41], off offset:-2048 nt
	v_pk_add_f32 v[82:83], v[82:83], v[82:83] op_sel:[0,1] op_sel_hi:[1,0]
	s_waitcnt vmcnt(0)
	v_and_b32_e32 v65, 0xffff0000, v39
	v_and_b32_e32 v64, 0xffff0000, v38
	v_lshlrev_b32_e32 v63, 16, v39
	v_lshlrev_b32_e32 v62, 16, v38
	v_pk_mul_f32 v[38:39], v[64:65], v[64:65]
	v_mov_b32_e32 v42, v82
	v_pk_fma_f32 v[38:39], v[62:63], v[62:63], v[38:39]
	s_nop 0
	v_pk_add_f32 v[84:85], v[38:39], v[38:39] op_sel:[0,1] op_sel_hi:[1,0]
	global_load_dwordx2 v[38:39], v[40:41], off offset:-1536 nt
	v_mov_b32_e32 v88, v84
	v_pk_add_f32 v[82:83], v[82:83], v[84:85]
	s_waitcnt vmcnt(0)
	v_and_b32_e32 v57, 0xffff0000, v39
	v_and_b32_e32 v56, 0xffff0000, v38
	v_lshlrev_b32_e32 v53, 16, v39
	v_lshlrev_b32_e32 v52, 16, v38
	v_pk_mul_f32 v[38:39], v[56:57], v[56:57]
	s_nop 0
	v_pk_fma_f32 v[86:87], v[52:53], v[52:53], v[38:39]
	global_load_dwordx2 v[38:39], v[40:41], off offset:-1024 nt
	s_waitcnt vmcnt(0)
	v_lshlrev_b32_e32 v44, 16, v38
	v_and_b32_e32 v45, 0xffff0000, v38
	v_lshlrev_b32_e32 v46, 16, v39
	v_and_b32_e32 v47, 0xffff0000, v39
	global_load_dwordx2 v[38:39], v[40:41], off offset:-512 nt
	s_waitcnt vmcnt(0)
	v_lshlrev_b32_e32 v43, 16, v38
	v_mov_b32_e32 v89, v43
	v_and_b32_e32 v41, 0xffff0000, v38
	v_pk_mul_f32 v[84:85], v[42:43], v[88:89]
	v_mul_f32_e32 v40, v41, v41
	v_mov_b32_e32 v83, v85
	v_pk_add_f32 v[84:85], v[86:87], v[86:87] op_sel:[0,1] op_sel_hi:[1,0]
	v_lshlrev_b32_e32 v38, 16, v39
	v_mov_b32_e32 v85, v40
	v_mul_f32_e32 v40, v45, v45
	v_and_b32_e32 v39, 0xffff0000, v39
	v_pk_add_f32 v[82:83], v[82:83], v[84:85]
	v_pk_fma_f32 v[84:85], v[44:45], v[44:45], v[40:41] op_sel_hi:[1,1,0]
	v_mul_f32_e32 v40, v47, v47
	v_mul_f32_e32 v50, v38, v38
	v_mul_f32_e32 v54, v39, v39
	v_pk_fma_f32 v[86:87], v[46:47], v[46:47], v[40:41] op_sel_hi:[1,1,0]
	v_mov_b32_e32 v85, v50
	v_mov_b32_e32 v87, v54
	v_pk_add_f32 v[84:85], v[84:85], v[86:87]
	v_mov_b32_e32 v50, v55
	v_pk_add_f32 v[82:83], v[82:83], v[84:85]
	s_nop 0
	v_add_f32_e32 v40, v82, v83
	ds_bpermute_b32 v42, v74, v40
	s_waitcnt lgkmcnt(0)
	v_add_f32_e32 v40, v40, v42
	ds_bpermute_b32 v42, v75, v40
	s_waitcnt lgkmcnt(0)
	v_add_f32_e32 v40, v40, v42
	ds_bpermute_b32 v42, v76, v40
	s_waitcnt lgkmcnt(0)
	v_add_f32_e32 v40, v40, v42
	ds_bpermute_b32 v42, v77, v40
	s_waitcnt lgkmcnt(0)
	v_add_f32_e32 v40, v40, v42
	ds_bpermute_b32 v42, v78, v40
	s_waitcnt lgkmcnt(0)
	v_add_f32_e32 v40, v40, v42
	ds_bpermute_b32 v42, v79, v40
	s_waitcnt lgkmcnt(0)
	v_add_f32_e32 v40, v40, v42
	v_fmamk_f32 v40, v40, 0x3a000000, v33
	v_cmp_gt_f32_e32 vcc, s3, v40
	v_mul_f32_e32 v42, 0x4b800000, v40
	s_nop 0
	v_cndmask_b32_e32 v40, v40, v42, vcc
	v_rsq_f32_e32 v40, v40
	s_nop 0
	v_mul_f32_e32 v42, 0x45800000, v40
	v_cndmask_b32_e32 v42, v40, v42, vcc
	v_and_b32_e32 v40, 0xffffe000, v32
	v_add_u32_e32 v54, v80, v40
	ds_read_b128 v[82:85], v54
	v_pk_mul_f32 v[66:67], v[42:43], v[66:67] op_sel_hi:[0,1]
	v_pk_mul_f32 v[68:69], v[42:43], v[68:69] op_sel_hi:[0,1]
	v_pk_mul_f32 v[50:51], v[50:51], v[42:43] op_sel_hi:[1,0]
	v_pk_mul_f32 v[48:49], v[48:49], v[42:43] op_sel_hi:[1,0]
	s_waitcnt lgkmcnt(0)
; #define LAS __attribute__((address_space(3)))
; __device__ __forceinline__ unsigned pk2(float lo, float hi) { return pg8::cvtpk(lo, hi); }
; __device__ __forceinline__ void p7_rows(const Params& P, LAS unsigned char* lds, int G) {
;     ...
;         for (int j = 0; j < 8; ++j) { const f32x4 a = *(const LAS f32x4*)(TA + b * DM + 256 * j + 4 * lane); const f32x4 x1 = xv[j] + v[j] * rstd * a; v[j] = x1; { u32x2 w; w.x = pk2(x1[0], x1[1]); w.y = pk2(x1[2], x1[3]); __builtin_nontemporal_store(w, x1r + 64 * j); }
;             s2 += (x1[0] * x1[0] + x1[1] * x1[1]) + (x1[2] * x1[2] + x1[3] * x1[3]); }
;         const float rstd2 = rsqrtf(wave_sum(s2) * (1.0f / DM) + RMS_EPS);
	v_pk_fma_f32 v[84:85], v[84:85], v[68:69], v[30:31]
	v_pk_fma_f32 v[82:83], v[82:83], v[66:67], v[28:29]
	v_cvt_pk_bf16_f32 v29, v84, v85
	v_cvt_pk_bf16_f32 v28, v82, v83
	global_store_dwordx2 v[36:37], v[28:29], off nt
	ds_read_b128 v[28:31], v54 offset:1024
	v_mov_b32_e32 v66, v70
	v_mov_b32_e32 v67, v72
	v_mov_b32_e32 v72, v71
	v_pk_mul_f32 v[66:67], v[42:43], v[66:67] op_sel_hi:[0,1]
	v_pk_mul_f32 v[68:69], v[42:43], v[72:73] op_sel_hi:[0,1]
	s_waitcnt lgkmcnt(0)
	v_pk_fma_f32 v[26:27], v[30:31], v[68:69], v[26:27]
	v_pk_fma_f32 v[28:29], v[28:29], v[66:67], v[24:25]
	v_cvt_pk_bf16_f32 v25, v26, v27
	v_cvt_pk_bf16_f32 v24, v28, v29
	v_mov_b32_e32 v30, v83
	v_mov_b32_e32 v31, v29
	global_store_dwordx2 v[36:37], v[24:25], off offset:512 nt
	v_mov_b32_e32 v24, v82
	v_mov_b32_e32 v25, v28
	v_pk_mul_f32 v[30:31], v[30:31], v[30:31]
	v_mov_b32_e32 v66, v85
	v_mov_b32_e32 v67, v27
	v_pk_fma_f32 v[24:25], v[24:25], v[24:25], v[30:31]
	v_mov_b32_e32 v30, v84
	v_mov_b32_e32 v31, v26
	v_pk_mul_f32 v[66:67], v[66:67], v[66:67]
	v_pk_mul_f32 v[44:45], v[42:43], v[44:45] op_sel_hi:[0,1]
	v_pk_fma_f32 v[30:31], v[30:31], v[30:31], v[66:67]
	ds_read_b128 v[66:69], v54 offset:2048
	v_pk_add_f32 v[24:25], v[24:25], v[30:31]
	v_pk_mul_f32 v[30:31], v[42:43], v[58:59] op_sel_hi:[0,1]
	v_pk_mul_f32 v[58:59], v[42:43], v[60:61] op_sel_hi:[0,1]
	v_pk_add_f32 v[24:25], v[24:25], v[24:25] op_sel_hi:[0,1]
	s_waitcnt lgkmcnt(0)
	v_pk_fma_f32 v[22:23], v[68:69], v[58:59], v[22:23]
	v_pk_fma_f32 v[20:21], v[66:67], v[30:31], v[20:21]
	v_cvt_pk_bf16_f32 v31, v22, v23
	v_cvt_pk_bf16_f32 v30, v20, v21
	global_store_dwordx2 v[36:37], v[30:31], off offset:1024 nt
	v_pk_mul_f32 v[30:31], v[22:23], v[22:23]
	v_pk_mul_f32 v[58:59], v[20:21], v[20:21]
	v_mov_b32_e32 v66, v62
	v_pk_mov_b32 v[60:61], v[58:59], v[30:31] op_sel:[1,0]
	v_mov_b32_e32 v59, v31
	v_pk_add_f32 v[30:31], v[60:61], v[58:59]
	ds_read_b128 v[58:61], v54 offset:3072
	v_mov_b32_e32 v67, v64
	v_mov_b32_e32 v64, v63
	v_pk_mul_f32 v[66:67], v[42:43], v[66:67] op_sel_hi:[0,1]
	v_pk_mul_f32 v[62:63], v[42:43], v[64:65] op_sel_hi:[0,1]
	s_waitcnt lgkmcnt(0)
	v_pk_fma_f32 v[18:19], v[60:61], v[48:49], v[18:19]
	v_pk_fma_f32 v[16:17], v[58:59], v[50:51], v[16:17]
	v_cvt_pk_bf16_f32 v49, v18, v19
	v_cvt_pk_bf16_f32 v48, v16, v17
	global_store_dwordx2 v[36:37], v[48:49], off offset:1536 nt
	ds_read_b128 v[48:51], v54 offset:4096
	v_mul_f32_e32 v24, v16, v16
	v_pk_fma_f32 v[58:59], v[16:17], v[16:17], v[24:25] op_sel_hi:[1,1,0]
	v_mul_f32_e32 v24, v18, v18
	v_pk_add_f32 v[30:31], v[30:31], v[30:31] op_sel_hi:[0,1]
	v_pk_fma_f32 v[60:61], v[18:19], v[18:19], v[24:25] op_sel_hi:[1,1,0]
	s_waitcnt lgkmcnt(0)
	v_pk_fma_f32 v[14:15], v[50:51], v[62:63], v[14:15]
	v_pk_fma_f32 v[12:13], v[48:49], v[66:67], v[12:13]
	v_cvt_pk_bf16_f32 v49, v14, v15
	v_cvt_pk_bf16_f32 v48, v12, v13
	v_mul_f32_e32 v58, v12, v12
	v_mul_f32_e32 v60, v13, v13
	v_mul_f32_e32 v30, v14, v14
	v_mul_f32_e32 v24, v15, v15
	global_store_dwordx2 v[36:37], v[48:49], off offset:2048 nt
	v_pk_add_f32 v[48:49], v[58:59], v[60:61]
	v_pk_add_f32 v[24:25], v[30:31], v[24:25]
	v_mov_b32_e32 v30, v52
	v_pk_add_f32 v[24:25], v[48:49], v[24:25]
	ds_read_b128 v[48:51], v54 offset:5120
	v_mov_b32_e32 v31, v56
	v_mov_b32_e32 v56, v53
	v_pk_mul_f32 v[30:31], v[42:43], v[30:31] op_sel_hi:[0,1]
	v_pk_mul_f32 v[52:53], v[42:43], v[56:57] op_sel_hi:[0,1]
	s_waitcnt lgkmcnt(0)
	v_pk_fma_f32 v[10:11], v[50:51], v[52:53], v[10:11]
	v_pk_fma_f32 v[8:9], v[48:49], v[30:31], v[8:9]
	v_cvt_pk_bf16_f32 v31, v10, v11
	v_cvt_pk_bf16_f32 v30, v8, v9
	global_store_dwordx2 v[36:37], v[30:31], off offset:2560 nt
	v_pk_mul_f32 v[30:31], v[10:11], v[10:11]
	v_pk_mul_f32 v[48:49], v[8:9], v[8:9]
	v_pk_mul_f32 v[46:47], v[42:43], v[46:47] op_sel_hi:[0,1]
	v_pk_mov_b32 v[50:51], v[48:49], v[30:31] op_sel:[1,0]
	v_mov_b32_e32 v49, v31
	v_pk_add_f32 v[30:31], v[50:51], v[48:49]
	ds_read_b128 v[48:51], v54 offset:6144
	v_pk_add_f32 v[24:25], v[24:25], v[24:25] op_sel_hi:[0,1]
	v_mov_b32_e32 v40, v43
	v_pk_mul_f32 v[40:41], v[40:41], v[42:43] op_sel_hi:[1,0]
	v_pk_mul_f32 v[38:39], v[38:39], v[42:43] op_sel_hi:[1,0]
	s_waitcnt lgkmcnt(0)
	v_pk_fma_f32 v[6:7], v[50:51], v[46:47], v[6:7]
	v_pk_fma_f32 v[4:5], v[48:49], v[44:45], v[4:5]
	v_cvt_pk_bf16_f32 v45, v6, v7
	v_cvt_pk_bf16_f32 v44, v4, v5
	global_store_dwordx2 v[36:37], v[44:45], off offset:3072 nt
	ds_read_b128 v[44:47], v54 offset:7168
	v_mul_f32_e32 v24, v4, v4
	v_pk_fma_f32 v[48:49], v[4:5], v[4:5], v[24:25] op_sel_hi:[1,1,0]
	v_mul_f32_e32 v24, v6, v6
	v_pk_add_f32 v[30:31], v[30:31], v[30:31] op_sel_hi:[0,1]
	v_pk_fma_f32 v[50:51], v[6:7], v[6:7], v[24:25] op_sel_hi:[1,1,0]
	s_waitcnt lgkmcnt(0)
	v_pk_fma_f32 v[2:3], v[46:47], v[38:39], v[2:3]
	v_pk_fma_f32 v[0:1], v[44:45], v[40:41], v[0:1]
	v_cvt_pk_bf16_f32 v39, v2, v3
	v_cvt_pk_bf16_f32 v38, v0, v1
	v_mul_f32_e32 v48, v0, v0
	v_mul_f32_e32 v50, v1, v1
	v_mul_f32_e32 v30, v2, v2
	v_mul_f32_e32 v24, v3, v3
	global_store_dwordx2 v[36:37], v[38:39], off offset:3584 nt
	v_pk_add_f32 v[38:39], v[48:49], v[50:51]
	v_pk_add_f32 v[24:25], v[30:31], v[24:25]
	v_add_u32_e32 v32, s42, v32
	v_pk_add_f32 v[24:25], v[38:39], v[24:25]
	ds_read_b128 v[38:41], v54 offset:16384
	ds_read_b128 v[42:45], v54 offset:32768
	v_add_f32_e32 v24, v24, v25
	ds_bpermute_b32 v25, v74, v24
	s_waitcnt lgkmcnt(0)
; #define LAS __attribute__((address_space(3)))
; __device__ __forceinline__ unsigned pk2(float lo, float hi) { return pg8::cvtpk(lo, hi); }
; __device__ __forceinline__ void p7_rows(const Params& P, LAS unsigned char* lds, int G) {
;     ...
;         const float rstd2 = rsqrtf(wave_sum(s2) * (1.0f / DM) + RMS_EPS);
;         u32x2* o = (u32x2*)(XN + (size_t)m * DM) + lane;
; #pragma unroll
;         for (int j = 0; j < 8; ++j) { const f32x4 a = *(const LAS f32x4*)(TB + b * DM + 256 * j + 4 * lane), c = *(const LAS f32x4*)(TC + b * DM + 256 * j + 4 * lane);
;             const f32x4 h = v[j] * rstd2 * a + c; u32x2 w; w.x = pk2(h[0], h[1]); w.y = pk2(h[2], h[3]); o[64 * j] = w; }
; __device__ __forceinline__ void xcd_barrier(const XcdBarrier& b) {
;     asm volatile("s_waitcnt vmcnt(0)" ::: "memory");
;     __syncthreads();
;     if (threadIdx.x == 0) {
;         unsigned* bar = b.bar;
;         __builtin_amdgcn_s_waitcnt(0);
;         unsigned nloc = b.st[0], nx = b.st[1];
;         if (nloc == 0u) { xcd_barrier_complete(bar, b.x, nloc, nx); b.st[0] = nloc; b.st[1] = nx; }
	v_add_f32_e32 v24, v24, v25
	ds_bpermute_b32 v25, v75, v24
	s_waitcnt lgkmcnt(0)
	v_add_f32_e32 v24, v24, v25
	ds_bpermute_b32 v25, v76, v24
	s_waitcnt lgkmcnt(0)
	v_add_f32_e32 v24, v24, v25
	ds_bpermute_b32 v25, v77, v24
	s_waitcnt lgkmcnt(0)
	v_add_f32_e32 v24, v24, v25
	ds_bpermute_b32 v25, v78, v24
	s_waitcnt lgkmcnt(0)
	v_add_f32_e32 v24, v24, v25
	ds_bpermute_b32 v25, v79, v24
	s_waitcnt lgkmcnt(0)
	v_add_f32_e32 v24, v24, v25
	v_fmamk_f32 v24, v24, 0x3a000000, v33
	v_cmp_gt_f32_e32 vcc, s3, v24
	v_mul_f32_e32 v25, 0x4b800000, v24
	s_nop 0
	v_cndmask_b32_e32 v24, v24, v25, vcc
	v_rsq_f32_e32 v24, v24
	s_nop 0
	v_mul_f32_e32 v25, 0x45800000, v24
	v_cndmask_b32_e32 v24, v24, v25, vcc
	v_pk_mul_f32 v[30:31], v[82:83], v[24:25] op_sel_hi:[1,0]
	v_pk_mul_f32 v[46:47], v[84:85], v[24:25] op_sel_hi:[1,0]
	v_pk_fma_f32 v[30:31], v[38:39], v[30:31], v[42:43]
	v_pk_fma_f32 v[40:41], v[40:41], v[46:47], v[44:45]
	v_add_co_u32_e32 v38, vcc, s33, v36
	v_cvt_pk_bf16_f32 v30, v30, v31
	v_cvt_pk_bf16_f32 v31, v40, v41
	v_addc_co_u32_e32 v39, vcc, -1, v37, vcc
	global_store_dwordx2 v[38:39], v[30:31], off
	ds_read_b128 v[38:41], v54 offset:17408
	ds_read_b128 v[42:45], v54 offset:33792
	v_pk_mul_f32 v[28:29], v[28:29], v[24:25] op_sel_hi:[1,0]
	v_pk_mul_f32 v[26:27], v[26:27], v[24:25] op_sel_hi:[1,0]
	s_mov_b32 s33, 0xec801000
	v_pk_mul_f32 v[20:21], v[20:21], v[24:25] op_sel_hi:[1,0]
	s_waitcnt lgkmcnt(0)
	v_pk_fma_f32 v[30:31], v[40:41], v[26:27], v[44:45]
	v_pk_fma_f32 v[26:27], v[38:39], v[28:29], v[42:43]
	v_pk_mul_f32 v[22:23], v[22:23], v[24:25] op_sel_hi:[1,0]
	v_cvt_pk_bf16_f32 v26, v26, v27
	v_cvt_pk_bf16_f32 v27, v30, v31
	v_add_co_u32_e32 v30, vcc, s33, v36
	v_pk_mul_f32 v[16:17], v[16:17], v[24:25] op_sel_hi:[1,0]
	s_nop 0
	v_addc_co_u32_e32 v31, vcc, -1, v37, vcc
	global_store_dwordx2 v[30:31], v[26:27], off offset:-3584
	ds_read_b128 v[26:29], v54 offset:18432
	ds_read_b128 v[38:41], v54 offset:34816
	v_pk_mul_f32 v[18:19], v[18:19], v[24:25] op_sel_hi:[1,0]
	v_pk_mul_f32 v[12:13], v[12:13], v[24:25] op_sel_hi:[1,0]
	v_pk_mul_f32 v[14:15], v[14:15], v[24:25] op_sel_hi:[1,0]
	v_pk_mul_f32 v[8:9], v[8:9], v[24:25] op_sel_hi:[1,0]
	s_waitcnt lgkmcnt(0)
	v_pk_fma_f32 v[22:23], v[28:29], v[22:23], v[40:41]
	v_pk_fma_f32 v[20:21], v[26:27], v[20:21], v[38:39]
	v_pk_mul_f32 v[10:11], v[10:11], v[24:25] op_sel_hi:[1,0]
	v_cvt_pk_bf16_f32 v20, v20, v21
	v_cvt_pk_bf16_f32 v21, v22, v23
	global_store_dwordx2 v[30:31], v[20:21], off offset:-3072
	ds_read_b128 v[20:23], v54 offset:19456
	ds_read_b128 v[26:29], v54 offset:35840
	v_pk_mul_f32 v[4:5], v[4:5], v[24:25] op_sel_hi:[1,0]
	v_pk_mul_f32 v[6:7], v[6:7], v[24:25] op_sel_hi:[1,0]
	v_pk_mul_f32 v[0:1], v[0:1], v[24:25] op_sel_hi:[1,0]
	v_pk_mul_f32 v[2:3], v[2:3], v[24:25] op_sel_hi:[1,0]
	s_waitcnt lgkmcnt(0)
	v_pk_fma_f32 v[18:19], v[22:23], v[18:19], v[28:29]
	v_pk_fma_f32 v[16:17], v[20:21], v[16:17], v[26:27]
	s_and_b32 s33, s2, 7
	s_lshl_b32 s33, s33, 11
	s_addk_i32 s33, 0x7ff
	s_cmpk_eq_u32 s92, 0x100
	s_cselect_b32 s33, s33, 0x3fff
	v_cvt_pk_bf16_f32 v16, v16, v17
	v_cvt_pk_bf16_f32 v17, v18, v19
	global_store_dwordx2 v[30:31], v[16:17], off offset:-2560
	ds_read_b128 v[16:19], v54 offset:20480
	ds_read_b128 v[20:23], v54 offset:36864
	v_cmp_lt_i32_e32 vcc, s33, v32
	v_lshl_add_u64 v[36:37], v[36:37], 0, s[26:27]
	s_or_b64 s[30:31], vcc, s[30:31]
	s_waitcnt lgkmcnt(0)
	v_pk_fma_f32 v[14:15], v[18:19], v[14:15], v[22:23]
	v_pk_fma_f32 v[12:13], v[16:17], v[12:13], v[20:21]
	s_nop 0
	v_cvt_pk_bf16_f32 v12, v12, v13
	v_cvt_pk_bf16_f32 v13, v14, v15
	global_store_dwordx2 v[30:31], v[12:13], off offset:-2048
	ds_read_b128 v[12:15], v54 offset:21504
	ds_read_b128 v[16:19], v54 offset:37888
	s_waitcnt lgkmcnt(0)
	v_pk_fma_f32 v[10:11], v[14:15], v[10:11], v[18:19]
	v_pk_fma_f32 v[8:9], v[12:13], v[8:9], v[16:17]
	s_nop 0
	v_cvt_pk_bf16_f32 v8, v8, v9
	v_cvt_pk_bf16_f32 v9, v10, v11
	global_store_dwordx2 v[30:31], v[8:9], off offset:-1536
	ds_read_b128 v[8:11], v54 offset:22528
	ds_read_b128 v[12:15], v54 offset:38912
	s_waitcnt lgkmcnt(0)
	v_pk_fma_f32 v[6:7], v[10:11], v[6:7], v[14:15]
	v_pk_fma_f32 v[4:5], v[8:9], v[4:5], v[12:13]
	s_nop 0
	v_cvt_pk_bf16_f32 v4, v4, v5
	v_cvt_pk_bf16_f32 v5, v6, v7
	global_store_dwordx2 v[30:31], v[4:5], off offset:-1024
	ds_read_b128 v[4:7], v54 offset:23552
	ds_read_b128 v[8:11], v54 offset:39936
	s_waitcnt lgkmcnt(0)
	v_pk_fma_f32 v[2:3], v[6:7], v[2:3], v[10:11]
	v_pk_fma_f32 v[0:1], v[4:5], v[0:1], v[8:9]
	s_nop 0
	v_cvt_pk_bf16_f32 v0, v0, v1
	v_cvt_pk_bf16_f32 v1, v2, v3
	global_store_dwordx2 v[30:31], v[0:1], off offset:-512
	s_andn2_b64 exec, exec, s[30:31]
	s_cbranch_execnz .LBB0_803
.LBB0_804:
	s_lshl_b32 s42, s92, 3
	s_or_b64 exec, exec, s[0:1]
	s_barrier
	s_waitcnt vmcnt(0)
	s_barrier
	s_mov_b64 s[0:1], exec
	v_readlane_b32 s22, v241, 0
	v_readlane_b32 s23, v241, 1
	s_and_b64 s[22:23], s[0:1], s[22:23]
	s_xor_b64 s[0:1], s[22:23], s[0:1]
	s_mov_b64 exec, s[22:23]
	s_cbranch_execz .LBB0_857
	s_add_i32 s3, 0, 0x20160
	v_mov_b32_e32 v0, s3
	s_waitcnt vmcnt(0) expcnt(0) lgkmcnt(0)
	ds_read_b32 v2, v0
	s_add_i32 s3, 0, 0x20164
	v_mov_b32_e32 v0, s3
	ds_read_b32 v0, v0
	s_waitcnt lgkmcnt(1)
	v_cmp_ne_u32_e32 vcc, 0, v2
	s_cbranch_vccnz .LBB0_820
	s_mov_b32 s3, 1
	v_mov_b32_e32 v16, 0
	s_branch .LBB0_808

; __device__ __forceinline__ void xcd_barrier(const XcdBarrier& b) {
;     ...
;     }
;     __syncthreads();
.Lgbar_end_8:
.LBB0_856:
	s_or_b64 exec, exec, s[22:23]

;     __host__ __device__ bool next(int i, Unit& u) const {
;         const long L = (long)i * G + c; if (L >= nwg) return false;
;         int wgid = (int)L; { const int q = nwg / NXCD, r = nwg % NXCD, xcd = wgid % NXCD, off = wgid / NXCD; wgid = (xcd < r ? xcd * (q + 1) : r * (q + 1) + (xcd - r) * q) + off; }
;         const int nig = WGM * nN, gid = wgid / nig, fm = gid * WGM, gsz = (nM - fm) < WGM ? (nM - fm) : WGM;
; __device__ __forceinline__ void xcd_barrier(const XcdBarrier& b) {
;     ...
;     __syncthreads();
.Lgbar_end_9:
.LBB0_925:
	s_or_b64 exec, exec, s[0:1]
	v_mov_b32_e32 v16, v168
	s_waitcnt lgkmcnt(0)
	s_barrier
	s_andn2_b64 vcc, exec, s[28:29]
	v_readfirstlane_b32 s28, v16
	s_cbranch_vccnz .LBB0_953
	s_ashr_i32 s3, s2, 31
	s_lshr_b32 s0, s3, 29
	s_add_i32 s21, s2, s0
	s_and_b32 s0, s21, -8
	s_sub_i32 s26, s2, s0
	s_cmp_gt_i32 s26, -1
	s_cbranch_scc0 .LBB0_928
	s_lshl_b32 s20, s26, 6
	s_ashr_i32 s21, s21, 3
	s_cbranch_execz .LBB0_929
	s_branch .LBB0_930

; __device__ __forceinline__ void p10_rows(const Params& P, LAS unsigned char* lds, int G) {
;     ...
;     for (int idx = tid; idx < 2 * DM; idx += NTHREADS) { const int b = idx >> 11, col = idx & (DM - 1); TA[idx] = ada[(size_t)b * NADA + 5 * DM + col] * P.g_post_ffn[col]; }
;     __syncthreads();
;     const bf16_t* F = (const bf16_t*)(P.ws + WS_O);
;     for (int m = blockIdx.x * 8 + wave; m < M; m += G * 8) {
;         const int b = m >> 13; const u32x2* fr = (const u32x2*)(F + (size_t)m * DM) + lane; f32x4* outr = (f32x4*)(P.out + (size_t)m * DM) + lane; const u32x2* x1r = (const u32x2*)((const bf16_t*)(P.ws + WS_X1) + (size_t)m * DM) + lane;
.Lgbar_end_10:
.LBB0_1005:
	s_or_b64 exec, exec, s[0:1]
	s_movk_i32 s0, 0x1000
	s_waitcnt lgkmcnt(0)
	s_barrier
	s_nop 0
	v_cmp_gt_i32_e32 vcc, s0, v168
	s_and_saveexec_b64 s[4:5], vcc
	s_cbranch_execz .LBB0_1019
	v_lshlrev_b32_e32 v0, 2, v168
	s_add_u32 s8, s48, 0x0
	s_addc_u32 s9, s49, 0
	global_load_dword v10, v0, s[8:9]
	s_add_u32 s8, s48, 0x800
	s_addc_u32 s9, s49, 0
	global_load_dword v11, v0, s[8:9]
	s_add_u32 s8, s48, 0x1000
	s_addc_u32 s9, s49, 0
	global_load_dword v12, v0, s[8:9]
	s_add_u32 s8, s48, 0x1800
	s_addc_u32 s9, s49, 0
	global_load_dword v13, v0, s[8:9]
	s_add_u32 s8, s58, 0x18a000
	s_addc_u32 s9, s59, 0
	global_load_dword v14, v0, s[8:9]
	s_add_u32 s8, s58, 0x18a800
	s_addc_u32 s9, s59, 0
	global_load_dword v15, v0, s[8:9]
	s_add_u32 s8, s58, 0x18b000
	s_addc_u32 s9, s59, 0
	global_load_dword v16, v0, s[8:9]
	s_add_u32 s8, s58, 0x18b800
	s_addc_u32 s9, s59, 0
	global_load_dword v17, v0, s[8:9]
	s_add_u32 s8, s58, 0x196000
	s_addc_u32 s9, s59, 0
	global_load_dword v18, v0, s[8:9]
	s_add_u32 s8, s58, 0x196800
	s_addc_u32 s9, s59, 0
	global_load_dword v19, v0, s[8:9]
	s_add_u32 s8, s58, 0x197000
	s_addc_u32 s9, s59, 0
	global_load_dword v20, v0, s[8:9]
	s_add_u32 s8, s58, 0x197800
	s_addc_u32 s9, s59, 0
	global_load_dword v21, v0, s[8:9]
	s_waitcnt vmcnt(7)
	v_mul_f32_e32 v22, v14, v10
	ds_write_b32 v0, v22
	s_waitcnt vmcnt(6)
	v_mul_f32_e32 v23, v15, v11
	ds_write_b32 v0, v23 offset:2048
	s_waitcnt vmcnt(5)
	v_mul_f32_e32 v24, v16, v12
	ds_write_b32 v0, v24 offset:4096
	s_waitcnt vmcnt(4)
	v_mul_f32_e32 v25, v17, v13
	ds_write_b32 v0, v25 offset:6144
	s_waitcnt vmcnt(3)
	v_mul_f32_e32 v26, v18, v10
	ds_write_b32 v0, v26 offset:8192
	s_waitcnt vmcnt(2)
	v_mul_f32_e32 v27, v19, v11
	ds_write_b32 v0, v27 offset:10240
	s_waitcnt vmcnt(1)
	v_mul_f32_e32 v28, v20, v12
	ds_write_b32 v0, v28 offset:12288
	s_waitcnt vmcnt(0)
	v_mul_f32_e32 v29, v21, v13
	ds_write_b32 v0, v29 offset:14336
.LBB0_1019:
	s_or_b64 exec, exec, s[4:5]
	v_ashrrev_i32_e32 v0, 6, v168
	v_readlane_b32 s0, v241, 15
	s_bfe_u32 s1, s0, 0x30003
	s_lshl_b32 s1, s1, 11
	s_lshr_b32 s98, s0, 6
	s_lshl_b32 s98, s98, 3
	s_add_i32 s98, s98, s1
	s_addk_i32 s1, 0x7ff
	s_cmpk_eq_u32 s92, 0x100
	s_cselect_b32 s0, s98, s0
	s_cselect_b32 s98, s1, 0x3fff
	s_waitcnt lgkmcnt(0)
	s_barrier
	v_add_u32_e32 v0, s0, v0
	s_movk_i32 s0, 0x4000
	v_cmp_gt_i32_e32 vcc, s0, v0
	s_and_saveexec_b64 s[2:3], vcc
	s_cbranch_execz .LBB0_1022
	v_mbcnt_hi_u32_b32 v1, -1, v208
	v_and_b32_e32 v2, 64, v1
	v_add_u32_e32 v2, 64, v2
	v_xor_b32_e32 v3, 1, v1
	v_cmp_lt_i32_e32 vcc, v3, v2
	v_and_b32_e32 v4, 63, v168
	v_lshlrev_b32_e32 v6, 4, v4
	v_cndmask_b32_e32 v3, v1, v3, vcc
	v_lshlrev_b32_e32 v24, 2, v3
	v_xor_b32_e32 v3, 2, v1
	v_cmp_lt_i32_e32 vcc, v3, v2
	s_mov_b64 s[0:1], 0x1a000000
	s_cmpk_eq_u32 s92, 0x100
	s_cselect_b32 s42, 0x100, s42
	s_ashr_i32 s43, s42, 31
	v_cndmask_b32_e32 v3, v1, v3, vcc
	v_lshlrev_b32_e32 v25, 2, v3
	v_xor_b32_e32 v3, 4, v1
	v_cmp_lt_i32_e32 vcc, v3, v2
	v_add_u32_e32 v30, 0, v6
	s_lshl_b64 s[4:5], s[42:43], 12
	v_cndmask_b32_e32 v3, v1, v3, vcc
	v_lshlrev_b32_e32 v26, 2, v3
	v_xor_b32_e32 v3, 8, v1
	v_cmp_lt_i32_e32 vcc, v3, v2
	s_lshl_b64 s[6:7], s[42:43], 13
	s_mov_b64 s[8:9], 0
	v_cndmask_b32_e32 v3, v1, v3, vcc
	v_lshlrev_b32_e32 v27, 2, v3
	v_xor_b32_e32 v3, 16, v1
	v_cmp_lt_i32_e32 vcc, v3, v2
	s_mov_b32 s10, 0xf0801000
	s_mov_b32 s11, 0x800000
	v_cndmask_b32_e32 v3, v1, v3, vcc
	v_lshlrev_b32_e32 v28, 2, v3
	v_xor_b32_e32 v3, 32, v1
	v_cmp_lt_i32_e32 vcc, v3, v2
	s_mov_b32 s12, s98
	s_nop 0
	v_cndmask_b32_e32 v1, v1, v3, vcc
	v_lshlrev_b32_e32 v29, 2, v1
	v_ashrrev_i32_e32 v1, 31, v0
	v_lshlrev_b64 v[2:3], 12, v[0:1]
	v_lshl_or_b32 v2, v4, 3, v2
	v_lshlrev_b64 v[4:5], 13, v[0:1]
	v_lshl_add_u64 v[2:3], s[58:59], 0, v[2:3]
	v_or_b32_e32 v4, v4, v6
	v_lshl_add_u64 v[2:3], v[2:3], 0, s[0:1]
	v_lshl_add_u64 v[4:5], s[56:57], 0, v[4:5]
	s_mov_b64 s[0:1], 0x1000
	v_lshl_add_u64 v[4:5], v[4:5], 0, s[0:1]
	v_mov_b32_e32 v1, 0x358637bd
